# P4 output pass: 6/10 split by workgroup group + the loop-invariant gain loads (and their vmcnt(0)) hoisted out of the item loop
# speedup vs baseline: 1.0026x; 1.0026x over previous
; __device__ __forceinline__ void phase_lru_diff_out(int l, KIn in, const bf16* __restrict__ proj, const bf16* __restrict__ LH, const bf16* __restrict__ CP, const float* __restrict__ HIN, ...
;     float s1 = 0.f, s2 = 0.f;
;     for (int i = 0; i < 32; ++i) { s1 += in[10][l * 32 + i] * in[11][l * 32 + i]; s2 += in[12][l * 32 + i] * in[13][l * 32 + i]; }
;     const float lam_init = 0.8f - 0.6f * expf(-0.3f * (float)l), lam = expf(s1) - expf(s2) + lam_init, osc = 1.f - lam_init;
;     const float* dn = in[14] + l * 64;
; #pragma unroll 2
;     for (int idx = gid; idx < T * 32; idx += gsz) {
;         const int row = idx >> 5;
;         const int c8 = (idx & 31) * 8, b = row >> 12, ch = (row & (SEQ - 1)) >> 6, h = (idx >> 3) & 3, v8 = (idx & 7) * 8;
;         const u32x4 rlh = *(const u32x4*)(LH + (size_t)row * 256 + c8), rcp = *(const u32x4*)(CP + (size_t)row * 256 + c8), rgt = *(const u32x4*)(proj + (size_t)row * PP + C_RG + c8);
;         const float* hp = HIN + (size_t)(b * 64 + ch) * 256 + c8; const f32x4 h0 = *(const f32x4*)hp, h1 = *(const f32x4*)(hp + 4);
.LBB0_721:
	v_mov_b32_e32 v0, v216
	s_mov_b64 s[28:29], s[0:1]
	s_mov_b32 s24, s56
	s_mov_b32 s25, s55
	s_cmp_lt_u32 s55, 0x80
	s_cselect_b32 s100, 0, 0x50000
	s_mov_b32 s101, 0xfffff
	s_cselect_b32 s101, 0x5ffff, s101
	s_mov_b32 s2, 0x100000
	v_lshl_add_u32 v34, s25, 9, v0
	v_add_u32_e32 v34, s100, v34
	s_lshl_b32 s100, s100, 3
	v_cmp_gt_i32_e32 vcc, s2, v34
	s_and_saveexec_b64 s[12:13], vcc
	s_mov_b32 s30, 0xfffff
	s_cbranch_execz .LBB0_724
	s_load_dwordx2 s[14:15], s[28:29], 0x118
	s_mov_b32 s2, 0x10000
	v_cvt_f32_u32_e32 v2, s66
	s_load_dwordx8 s[4:11], s[28:29], 0x50
	s_nop 0
	s_load_dwordx2 s[28:29], s[28:29], 0x70
	s_mov_b32 s3, 0x3fb8aa3b
	s_waitcnt lgkmcnt(0)
	s_add_u32 s16, s14, 0x1b800000
	s_addc_u32 s17, s15, 0
	s_add_u32 s18, s14, 0x1c800000
	s_addc_u32 s19, s15, 0
	s_add_u32 s20, s14, 0x380000
	s_addc_u32 s21, s15, 0
	v_mul_f32_e32 v2, 0xbe99999a, v2
	s_add_u32 s22, s14, 0x1d800000
	v_mul_f32_e32 v3, 0x3fb8aa3b, v2
	s_addc_u32 s23, s15, 0
	v_fma_f32 v4, v2, s3, -v3
	v_rndne_f32_e32 v5, v3
	s_add_u32 s26, s14, 0x17800000
	v_fmac_f32_e32 v4, 0x32a5705f, v2
	v_sub_f32_e32 v3, v3, v5
	s_addc_u32 s27, s15, 0
	v_add_f32_e32 v3, v3, v4
	s_lshl_b64 s[38:39], s[70:71], 2
	v_exp_f32_e32 v3, v3
	v_cvt_i32_f32_e32 v4, v5
	s_add_u32 s28, s28, s38
	s_addc_u32 s29, s29, s39
	s_lshl_b32 s34, s66, 5
	s_lshl_b64 s[70:71], s[34:35], 2
	s_mov_b32 s33, 0xc2ce8ed0
	s_add_u32 s4, s4, s70
	v_ldexp_f32 v3, v3, v4
	v_cmp_ngt_f32_e32 vcc, s33, v2
	s_mov_b32 s40, 0x42b17218
	s_addc_u32 s5, s5, s71
	v_cndmask_b32_e32 v3, 0, v3, vcc
	v_cmp_nlt_f32_e32 vcc, s40, v2
	v_mov_b32_e32 v39, 0x7f800000
	s_add_u32 s6, s6, s70
	v_cndmask_b32_e32 v2, v39, v3, vcc
	v_mov_b32_e32 v3, 0x3f4ccccd
	s_addc_u32 s7, s7, s71
	v_fmamk_f32 v36, v2, 0xbf19999a, v3
	global_load_dwordx4 v[2:5], v1, s[4:5] offset:48
	global_load_dwordx4 v[6:9], v1, s[4:5] offset:32
	global_load_dwordx4 v[10:13], v1, s[4:5] offset:16
	global_load_dwordx4 v[14:17], v1, s[4:5]
	global_load_dwordx4 v[18:21], v1, s[6:7] offset:48
	global_load_dwordx4 v[22:25], v1, s[6:7] offset:32
	global_load_dwordx4 v[26:29], v1, s[6:7] offset:16
	global_load_dwordx4 v[30:33], v1, s[6:7]
	v_lshlrev_b32_e32 v0, 3, v0
	v_sub_f32_e32 v35, 1.0, v36
	s_waitcnt vmcnt(0)
	v_fma_f32 v37, v14, v30, 0
	v_fmac_f32_e32 v37, v15, v31
	v_fmac_f32_e32 v37, v16, v32
	v_fmac_f32_e32 v37, v17, v33
	v_fmac_f32_e32 v37, v10, v26
	v_fmac_f32_e32 v37, v11, v27
	v_fmac_f32_e32 v37, v12, v28
	v_fmac_f32_e32 v37, v13, v29
	v_fmac_f32_e32 v37, v6, v22
	v_fmac_f32_e32 v37, v7, v23
	v_fmac_f32_e32 v37, v8, v24
	v_fmac_f32_e32 v37, v9, v25
	v_fmac_f32_e32 v37, v2, v18
	v_fmac_f32_e32 v37, v3, v19
	v_fmac_f32_e32 v37, v4, v20
	v_fmac_f32_e32 v37, v5, v21
	global_load_dwordx4 v[2:5], v1, s[4:5] offset:112
	global_load_dwordx4 v[6:9], v1, s[4:5] offset:96
	global_load_dwordx4 v[10:13], v1, s[4:5] offset:80
	global_load_dwordx4 v[14:17], v1, s[4:5] offset:64
	global_load_dwordx4 v[18:21], v1, s[6:7] offset:112
	global_load_dwordx4 v[22:25], v1, s[6:7] offset:96
	global_load_dwordx4 v[26:29], v1, s[6:7] offset:80
	global_load_dwordx4 v[30:33], v1, s[6:7] offset:64
	s_add_u32 s6, s8, s70
	s_addc_u32 s7, s9, s71
	s_add_u32 s4, s10, s70
	s_addc_u32 s5, s11, s71
	s_waitcnt vmcnt(0)
	v_fmac_f32_e32 v37, v14, v30
	v_fmac_f32_e32 v37, v15, v31
	v_fmac_f32_e32 v37, v16, v32
	v_fmac_f32_e32 v37, v17, v33
	v_fmac_f32_e32 v37, v10, v26
	v_fmac_f32_e32 v37, v11, v27
	v_fmac_f32_e32 v37, v12, v28
	v_fmac_f32_e32 v37, v13, v29
	v_fmac_f32_e32 v37, v6, v22
	v_fmac_f32_e32 v37, v7, v23
	v_fmac_f32_e32 v37, v8, v24
	v_fmac_f32_e32 v37, v9, v25
	v_fmac_f32_e32 v37, v2, v18
	v_fmac_f32_e32 v37, v3, v19
	v_fmac_f32_e32 v37, v4, v20
	v_fmac_f32_e32 v37, v5, v21
	v_mul_f32_e32 v2, 0x3fb8aa3b, v37
	v_fma_f32 v3, v37, s3, -v2
	v_rndne_f32_e32 v4, v2
	v_fmac_f32_e32 v3, 0x32a5705f, v37
	v_sub_f32_e32 v2, v2, v4
	v_add_f32_e32 v2, v2, v3
	v_exp_f32_e32 v2, v2
	v_cvt_i32_f32_e32 v3, v4
	v_cmp_ngt_f32_e32 vcc, s33, v37
	v_ldexp_f32 v2, v2, v3
	s_nop 0
	v_cndmask_b32_e32 v2, 0, v2, vcc
	v_cmp_nlt_f32_e32 vcc, s40, v37
	s_nop 1
	v_cndmask_b32_e32 v37, v39, v2, vcc
	global_load_dwordx4 v[2:5], v1, s[6:7] offset:48
	global_load_dwordx4 v[6:9], v1, s[6:7] offset:32
	global_load_dwordx4 v[10:13], v1, s[6:7] offset:16
	global_load_dwordx4 v[14:17], v1, s[6:7]
	global_load_dwordx4 v[18:21], v1, s[4:5] offset:48
	global_load_dwordx4 v[22:25], v1, s[4:5] offset:32
	global_load_dwordx4 v[26:29], v1, s[4:5] offset:16
	global_load_dwordx4 v[30:33], v1, s[4:5]
	s_waitcnt vmcnt(0)
	v_fma_f32 v38, v14, v30, 0
	v_fmac_f32_e32 v38, v15, v31
	v_fmac_f32_e32 v38, v16, v32
	v_fmac_f32_e32 v38, v17, v33
	v_fmac_f32_e32 v38, v10, v26
	v_fmac_f32_e32 v38, v11, v27
	v_fmac_f32_e32 v38, v12, v28
	v_fmac_f32_e32 v38, v13, v29
	v_fmac_f32_e32 v38, v6, v22
	v_fmac_f32_e32 v38, v7, v23
	v_fmac_f32_e32 v38, v8, v24
	v_fmac_f32_e32 v38, v9, v25
	v_fmac_f32_e32 v38, v2, v18
	v_fmac_f32_e32 v38, v3, v19
	v_fmac_f32_e32 v38, v4, v20
	v_fmac_f32_e32 v38, v5, v21
	global_load_dwordx4 v[2:5], v1, s[6:7] offset:112
	global_load_dwordx4 v[10:13], v1, s[6:7] offset:96
	global_load_dwordx4 v[18:21], v1, s[6:7] offset:80
	global_load_dwordx4 v[26:29], v1, s[6:7] offset:64
	global_load_dwordx4 v[6:9], v1, s[4:5] offset:112
	global_load_dwordx4 v[14:17], v1, s[4:5] offset:96
	global_load_dwordx4 v[22:25], v1, s[4:5] offset:80
	global_load_dwordx4 v[30:33], v1, s[4:5] offset:64
	s_mov_b32 s6, 0x80000
	s_mov_b64 s[4:5], 0
	s_waitcnt vmcnt(0)
; __device__ __forceinline__ u32x4 pack8(const float* f) { u32x4 w; w.x = pk2(f[0], f[1]); w.y = pk2(f[2], f[3]); w.z = pk2(f[4], f[5]); w.w = pk2(f[6], f[7]); return w; }
; __device__ __forceinline__ float gelu_tanh(float x) { return x / (1.f + __expf(-1.5957691216057308f * (x + 0.044715f * x * x * x))); }
; __device__ __forceinline__ void phase_lru_diff_out(int l, KIn in, const bf16* __restrict__ proj, const bf16* __restrict__ LH, const bf16* __restrict__ CP, const float* __restrict__ HIN, ...
;     ...
;     for (int idx = gid; idx < T * 32; idx += gsz) {
;         const int row = idx >> 5;
;         const int c8 = (idx & 31) * 8, b = row >> 12, ch = (row & (SEQ - 1)) >> 6, h = (idx >> 3) & 3, v8 = (idx & 7) * 8;
;         const u32x4 rlh = *(const u32x4*)(LH + (size_t)row * 256 + c8), rcp = *(const u32x4*)(CP + (size_t)row * 256 + c8), rgt = *(const u32x4*)(proj + (size_t)row * PP + C_RG + c8);
;         const float* hp = HIN + (size_t)(b * 64 + ch) * 256 + c8; const f32x4 h0 = *(const f32x4*)hp, h1 = *(const f32x4*)(hp + 4);
;         const u32x4 ra = *(const u32x4*)(OP + (size_t)row * 512 + (2 * h) * 64 + v8), rb = *(const u32x4*)(OP + (size_t)row * 512 + (2 * h + 1) * 64 + v8);
;         { float lh[8], cp[8], gt[8], o[8]; unpack8(rlh, lh); unpack8(rcp, cp); unpack8(rgt, gt);
;           const float hin[8] = {h0.x, h0.y, h0.z, h0.w, h1.x, h1.y, h1.z, h1.w};
; #pragma unroll
;           for (int e = 0; e < 8; ++e) o[e] = (lh[e] + cp[e] * hin[e]) * gelu_tanh(gt[e]);
;           *(u32x4*)(MIXO + (size_t)row * DM + 768 + c8) = pack8(o); }
	v_fmac_f32_e32 v38, v26, v30
	v_fmac_f32_e32 v38, v27, v31
	v_fmac_f32_e32 v38, v28, v32
	v_fmac_f32_e32 v38, v29, v33
	v_fmac_f32_e32 v38, v18, v22
	v_fmac_f32_e32 v38, v19, v23
	v_fmac_f32_e32 v38, v20, v24
	v_fmac_f32_e32 v38, v21, v25
	v_fmac_f32_e32 v38, v10, v14
	v_fmac_f32_e32 v38, v11, v15
	v_fmac_f32_e32 v38, v12, v16
	v_fmac_f32_e32 v38, v13, v17
	v_fmac_f32_e32 v38, v2, v6
	v_fmac_f32_e32 v38, v3, v7
	v_fmac_f32_e32 v38, v4, v8
	v_fmac_f32_e32 v38, v5, v9
	v_mul_f32_e32 v2, 0x3fb8aa3b, v38
	v_fma_f32 v3, v38, s3, -v2
	v_rndne_f32_e32 v4, v2
	v_fmac_f32_e32 v3, 0x32a5705f, v38
	v_sub_f32_e32 v2, v2, v4
	v_add_f32_e32 v2, v2, v3
	v_exp_f32_e32 v2, v2
	v_cvt_i32_f32_e32 v3, v4
	v_cmp_ngt_f32_e32 vcc, s33, v38
	v_lshl_add_u32 v29, s25, 12, v0
	v_add_u32_e32 v29, s100, v29
	v_ldexp_f32 v2, v2, v3
	v_cndmask_b32_e32 v2, 0, v2, vcc
	v_cmp_nlt_f32_e32 vcc, s40, v38
	v_and_b32_e32 v3, 64, v241
	v_add_u32_e32 v3, 64, v3
	v_cndmask_b32_e32 v2, v39, v2, vcc
	v_sub_f32_e32 v2, v37, v2
	v_add_f32_e32 v18, v36, v2
	v_xor_b32_e32 v2, 1, v241
	v_cmp_lt_i32_e32 vcc, v2, v3
	v_mov_b32_e32 v19, v18
	s_nop 0
	v_cndmask_b32_e32 v2, v241, v2, vcc
	v_lshlrev_b32_e32 v26, 2, v2
	v_xor_b32_e32 v2, 2, v241
	v_cmp_lt_i32_e32 vcc, v2, v3
	s_nop 1
	v_cndmask_b32_e32 v2, v241, v2, vcc
	v_lshlrev_b32_e32 v27, 2, v2
	v_xor_b32_e32 v2, 4, v241
	v_cmp_lt_i32_e32 vcc, v2, v3
	s_nop 1
	v_cndmask_b32_e32 v2, v241, v2, vcc
	v_lshlrev_b32_e32 v28, 2, v2
	v_and_b32_e32 v180, 56, v29
	v_lshlrev_b32_e32 v180, 2, v180
	global_load_dwordx4 v[164:167], v180, s[28:29] offset:16
	global_load_dwordx4 v[176:179], v180, s[28:29]
.LBB0_723:
	v_ashrrev_i32_e32 v24, 5, v34
	v_ashrrev_i32_e32 v25, 31, v24
	v_and_b32_e32 v6, 0xf8, v29
	v_lshlrev_b64 v[2:3], 9, v[24:25]
	v_lshl_add_u64 v[4:5], s[16:17], 0, v[2:3]
	v_lshlrev_b32_e32 v0, 1, v6
	v_lshl_add_u64 v[2:3], s[18:19], 0, v[2:3]
	v_lshl_add_u64 v[4:5], v[4:5], 0, v[0:1]
	v_lshl_add_u64 v[2:3], v[2:3], 0, v[0:1]
	global_load_dwordx4 v[10:13], v[4:5], off
	global_load_dwordx4 v[14:17], v[2:3], off
	v_mov_b64_e32 v[2:3], s[14:15]
	v_mad_i64_i32 v[2:3], s[8:9], v24, s88, v[2:3]
	v_lshl_add_u64 v[2:3], v[2:3], 0, v[0:1]
	s_mov_b32 s3, 0xd801000
	v_add_co_u32_e32 v2, vcc, s3, v2
	v_lshrrev_b32_e32 v7, 6, v24
	s_nop 0
	v_addc_co_u32_e32 v3, vcc, 0, v3, vcc
	global_load_dwordx4 v[36:39], v[2:3], off
	v_ashrrev_i32_e32 v2, 11, v34
	v_bfi_b32 v2, 63, v7, v2
	v_ashrrev_i32_e32 v3, 31, v2
	v_lshlrev_b64 v[2:3], 10, v[2:3]
	v_lshl_add_u64 v[2:3], s[20:21], 0, v[2:3]
	v_lshlrev_b32_e32 v4, 2, v6
	v_mov_b32_e32 v5, v1
	v_lshl_add_u64 v[2:3], v[2:3], 0, v[4:5]
	global_load_dwordx4 v[40:43], v[2:3], off offset:16
	global_load_dwordx4 v[44:47], v[2:3], off
	v_bfe_u32 v8, v34, 3, 2
	v_lshlrev_b64 v[2:3], 10, v[24:25]
	v_and_b32_e32 v30, 56, v29
	v_lshl_add_u64 v[2:3], s[22:23], 0, v[2:3]
	v_lshlrev_b32_e32 v4, 8, v8
	v_lshl_add_u64 v[2:3], v[2:3], 0, v[4:5]
	v_lshlrev_b32_e32 v22, 1, v30
	v_mov_b32_e32 v23, v1
	v_lshl_add_u64 v[2:3], v[2:3], 0, v[22:23]
	v_lshlrev_b32_e32 v20, 7, v8
	global_load_dwordx4 v[6:9], v[2:3], off
	s_nop 0
	global_load_dwordx4 v[2:5], v[2:3], off offset:128
	v_mov_b32_e32 v21, v1
	v_add_u32_e32 v34, s2, v34
	v_add_u32_e32 v29, s6, v29
	s_waitcnt vmcnt(6)
	v_lshlrev_b32_e32 v32, 16, v10
	v_and_b32_e32 v33, 0xffff0000, v10
	s_waitcnt vmcnt(5)
	v_lshlrev_b32_e32 v48, 16, v14
	v_and_b32_e32 v49, 0xffff0000, v14
	s_waitcnt vmcnt(4)
	v_lshlrev_b32_e32 v10, 16, v36
	v_mul_f32_e32 v31, 0x3d372713, v10
	v_mul_f32_e32 v31, v31, v10
	v_fma_f32 v31, v31, v10, v10
	v_mul_f32_e32 v31, 0xbfcc422a, v31
	v_and_b32_e32 v14, 0xffff0000, v36
	v_mul_f32_e32 v31, 0x3fb8aa3b, v31
	v_exp_f32_e32 v50, v31
	v_mul_f32_e32 v31, 0x3d372713, v14
	v_mul_f32_e32 v31, v31, v14
	v_fma_f32 v31, v31, v14, v14
	v_mul_f32_e32 v31, 0xbfcc422a, v31
	v_mul_f32_e32 v31, 0x3fb8aa3b, v31
	v_exp_f32_e32 v51, v31
	s_waitcnt vmcnt(2)
	v_pk_fma_f32 v[32:33], v[44:45], v[48:49], v[32:33]
	v_pk_add_f32 v[44:45], v[50:51], 1.0 op_sel_hi:[1,0]
	s_nop 0
	v_div_scale_f32 v31, s[8:9], v45, v45, v14
	v_rcp_f32_e32 v36, v31
	s_nop 0
	v_fma_f32 v48, -v31, v36, 1.0
	v_fmac_f32_e32 v36, v48, v36
	v_div_scale_f32 v48, vcc, v14, v45, v14
	v_mul_f32_e32 v49, v48, v36
	v_fma_f32 v50, -v31, v49, v48
	v_fmac_f32_e32 v49, v50, v36
	v_fma_f32 v31, -v31, v49, v48
	v_div_fmas_f32 v31, v31, v36, v49
	v_div_fixup_f32 v45, v31, v45, v14
	v_div_scale_f32 v14, s[8:9], v44, v44, v10
	v_rcp_f32_e32 v31, v14
	s_nop 0
	v_fma_f32 v36, -v14, v31, 1.0
	v_fmac_f32_e32 v31, v36, v31
	v_div_scale_f32 v36, vcc, v10, v44, v10
	v_mul_f32_e32 v48, v36, v31
	v_fma_f32 v49, -v14, v48, v36
	v_fmac_f32_e32 v48, v49, v31
	v_fma_f32 v14, -v14, v48, v36
	v_div_fmas_f32 v14, v14, v31, v48
	v_div_fixup_f32 v44, v14, v44, v10
	v_pk_mul_f32 v[32:33], v[32:33], v[44:45]
	v_lshlrev_b32_e32 v10, 16, v11
	v_and_b32_e32 v11, 0xffff0000, v11
	v_lshlrev_b32_e32 v14, 16, v15
	v_and_b32_e32 v15, 0xffff0000, v15
	v_lshlrev_b32_e32 v31, 16, v37
	v_and_b32_e32 v44, 0xffff0000, v37
	v_mul_f32_e32 v36, 0x3d372713, v31
	v_pk_fma_f32 v[10:11], v[46:47], v[14:15], v[10:11]
	v_mul_f32_e32 v14, 0x3d372713, v44
	v_mul_f32_e32 v36, v36, v31
	v_mul_f32_e32 v14, v14, v44
	v_fma_f32 v36, v36, v31, v31
	v_fma_f32 v14, v14, v44, v44
	v_mul_f32_e32 v36, 0xbfcc422a, v36
	v_mul_f32_e32 v14, 0xbfcc422a, v14
	v_mul_f32_e32 v36, 0x3fb8aa3b, v36
	v_mul_f32_e32 v14, 0x3fb8aa3b, v14
	v_exp_f32_e32 v36, v36
	v_exp_f32_e32 v37, v14
	s_nop 0
	v_pk_add_f32 v[14:15], v[36:37], 1.0 op_sel_hi:[1,0]
	s_nop 0
	v_div_scale_f32 v36, s[8:9], v15, v15, v44
	v_rcp_f32_e32 v37, v36
	s_nop 0
	v_fma_f32 v45, -v36, v37, 1.0
	v_fmac_f32_e32 v37, v45, v37
; __device__ __forceinline__ u32x4 pack8(const float* f) { u32x4 w; w.x = pk2(f[0], f[1]); w.y = pk2(f[2], f[3]); w.z = pk2(f[4], f[5]); w.w = pk2(f[6], f[7]); return w; }
; __device__ __forceinline__ float gelu_tanh(float x) { return x / (1.f + __expf(-1.5957691216057308f * (x + 0.044715f * x * x * x))); }
; __device__ __forceinline__ void phase_lru_diff_out(int l, KIn in, const bf16* __restrict__ proj, const bf16* __restrict__ LH, const bf16* __restrict__ CP, const float* __restrict__ HIN, ...
;     ...
;         { float lh[8], cp[8], gt[8], o[8]; unpack8(rlh, lh); unpack8(rcp, cp); unpack8(rgt, gt);
;           const float hin[8] = {h0.x, h0.y, h0.z, h0.w, h1.x, h1.y, h1.z, h1.w};
; #pragma unroll
;           for (int e = 0; e < 8; ++e) o[e] = (lh[e] + cp[e] * hin[e]) * gelu_tanh(gt[e]);
;           *(u32x4*)(MIXO + (size_t)row * DM + 768 + c8) = pack8(o); }
;         { float a[8], bq[8], o[8]; unpack8(ra, a); unpack8(rb, bq); float ss = 0.f;
; #pragma unroll
;           for (int e = 0; e < 8; ++e) { o[e] = a[e] - lam * bq[e]; ss += o[e] * o[e]; }
;           ss += __shfl_xor(ss, 1); ss += __shfl_xor(ss, 2); ss += __shfl_xor(ss, 4);
;           const float rstd = rsqrtf(ss * (1.f / 64.f) + EPS) * osc;
; #pragma unroll
;           for (int e = 0; e < 8; ++e) o[e] = o[e] * rstd * dn[v8 + e];
;           *(u32x4*)(MIXO + (size_t)row * DM + 256 + h * 64 + v8) = pack8(o); }
;     }
	v_div_scale_f32 v45, vcc, v44, v15, v44
	v_mul_f32_e32 v46, v45, v37
	v_fma_f32 v47, -v36, v46, v45
	v_fmac_f32_e32 v46, v47, v37
	v_fma_f32 v36, -v36, v46, v45
	v_div_fmas_f32 v36, v36, v37, v46
	v_div_fixup_f32 v15, v36, v15, v44
	v_div_scale_f32 v36, s[8:9], v14, v14, v31
	v_rcp_f32_e32 v37, v36
	s_nop 0
	v_fma_f32 v44, -v36, v37, 1.0
	v_fmac_f32_e32 v37, v44, v37
	v_div_scale_f32 v44, vcc, v31, v14, v31
	v_mul_f32_e32 v45, v44, v37
	v_fma_f32 v46, -v36, v45, v44
	v_fmac_f32_e32 v45, v46, v37
	v_fma_f32 v36, -v36, v45, v44
	v_div_fmas_f32 v36, v36, v37, v45
	v_div_fixup_f32 v14, v36, v14, v31
	v_pk_mul_f32 v[10:11], v[10:11], v[14:15]
	v_lshlrev_b32_e32 v14, 16, v12
	v_and_b32_e32 v15, 0xffff0000, v12
	v_lshlrev_b32_e32 v12, 16, v38
	v_mul_f32_e32 v31, 0x3d372713, v12
	v_mul_f32_e32 v31, v31, v12
	v_fma_f32 v31, v31, v12, v12
	v_mul_f32_e32 v31, 0xbfcc422a, v31
	v_lshlrev_b32_e32 v36, 16, v16
	v_and_b32_e32 v37, 0xffff0000, v16
	v_and_b32_e32 v16, 0xffff0000, v38
	v_mul_f32_e32 v31, 0x3fb8aa3b, v31
	v_exp_f32_e32 v44, v31
	v_mul_f32_e32 v31, 0x3d372713, v16
	v_mul_f32_e32 v31, v31, v16
	v_fma_f32 v31, v31, v16, v16
	v_mul_f32_e32 v31, 0xbfcc422a, v31
	v_mul_f32_e32 v31, 0x3fb8aa3b, v31
	v_exp_f32_e32 v45, v31
	v_pk_fma_f32 v[14:15], v[40:41], v[36:37], v[14:15]
	v_pk_add_f32 v[36:37], v[44:45], 1.0 op_sel_hi:[1,0]
	s_nop 0
	v_div_scale_f32 v31, s[8:9], v37, v37, v16
	v_rcp_f32_e32 v38, v31
	s_nop 0
	v_fma_f32 v40, -v31, v38, 1.0
	v_fmac_f32_e32 v38, v40, v38
	v_div_scale_f32 v40, vcc, v16, v37, v16
	v_mul_f32_e32 v41, v40, v38
	v_fma_f32 v44, -v31, v41, v40
	v_fmac_f32_e32 v41, v44, v38
	v_fma_f32 v31, -v31, v41, v40
	v_div_fmas_f32 v31, v31, v38, v41
	v_div_fixup_f32 v37, v31, v37, v16
	v_div_scale_f32 v16, s[8:9], v36, v36, v12
	v_rcp_f32_e32 v31, v16
	s_nop 0
	v_fma_f32 v38, -v16, v31, 1.0
	v_fmac_f32_e32 v31, v38, v31
	v_div_scale_f32 v38, vcc, v12, v36, v12
	v_mul_f32_e32 v40, v38, v31
	v_fma_f32 v41, -v16, v40, v38
	v_fmac_f32_e32 v40, v41, v31
	v_fma_f32 v16, -v16, v40, v38
	v_div_fmas_f32 v16, v16, v31, v40
	v_div_fixup_f32 v36, v16, v36, v12
	v_pk_mul_f32 v[36:37], v[14:15], v[36:37]
	v_lshlrev_b32_e32 v12, 16, v13
	v_and_b32_e32 v13, 0xffff0000, v13
	v_lshlrev_b32_e32 v14, 16, v17
	v_and_b32_e32 v15, 0xffff0000, v17
	v_lshlrev_b32_e32 v31, 16, v39
	v_and_b32_e32 v38, 0xffff0000, v39
	v_mul_f32_e32 v16, 0x3d372713, v31
	v_pk_fma_f32 v[12:13], v[42:43], v[14:15], v[12:13]
	v_mul_f32_e32 v14, 0x3d372713, v38
	v_mul_f32_e32 v16, v16, v31
	v_mul_f32_e32 v14, v14, v38
	v_fma_f32 v16, v16, v31, v31
	v_fma_f32 v14, v14, v38, v38
	v_mul_f32_e32 v16, 0xbfcc422a, v16
	v_mul_f32_e32 v14, 0xbfcc422a, v14
	v_mul_f32_e32 v16, 0x3fb8aa3b, v16
	v_mul_f32_e32 v14, 0x3fb8aa3b, v14
	v_exp_f32_e32 v16, v16
	v_exp_f32_e32 v17, v14
	s_nop 0
	v_pk_add_f32 v[14:15], v[16:17], 1.0 op_sel_hi:[1,0]
	s_nop 0
	v_div_scale_f32 v16, s[8:9], v15, v15, v38
	v_rcp_f32_e32 v17, v16
	s_nop 0
	v_fma_f32 v39, -v16, v17, 1.0
	v_fmac_f32_e32 v17, v39, v17
	v_div_scale_f32 v39, vcc, v38, v15, v38
	v_mul_f32_e32 v40, v39, v17
	v_fma_f32 v41, -v16, v40, v39
	v_fmac_f32_e32 v40, v41, v17
	v_fma_f32 v16, -v16, v40, v39
	v_div_fmas_f32 v16, v16, v17, v40
	v_div_fixup_f32 v15, v16, v15, v38
	v_div_scale_f32 v16, s[8:9], v14, v14, v31
	v_rcp_f32_e32 v17, v16
	s_waitcnt vmcnt(1)
	v_and_b32_e32 v41, 0xffff0000, v6
	v_fma_f32 v38, -v16, v17, 1.0
	v_fmac_f32_e32 v17, v38, v17
	v_div_scale_f32 v38, vcc, v31, v14, v31
	v_mul_f32_e32 v39, v38, v17
	v_fma_f32 v40, -v16, v39, v38
	v_fmac_f32_e32 v39, v40, v17
	v_fma_f32 v16, -v16, v39, v38
	v_div_fmas_f32 v16, v16, v17, v39
	v_div_fixup_f32 v14, v16, v14, v31
	v_pk_mul_f32 v[12:13], v[12:13], v[14:15]
	v_cvt_pk_bf16_f32 v15, v10, v11
	v_lshlrev_b64 v[10:11], 11, v[24:25]
	v_cvt_pk_bf16_f32 v17, v12, v13
	v_lshl_add_u64 v[12:13], s[26:27], 0, v[10:11]
	v_cvt_pk_bf16_f32 v14, v32, v33
	v_cvt_pk_bf16_f32 v16, v36, v37
	v_lshl_add_u64 v[10:11], v[12:13], 0, v[0:1]
	global_store_dwordx4 v[10:11], v[14:17], off offset:1536
	v_lshlrev_b32_e32 v10, 16, v9
	v_and_b32_e32 v11, 0xffff0000, v9
	s_waitcnt vmcnt(1)
	v_lshlrev_b32_e32 v14, 16, v5
	v_and_b32_e32 v15, 0xffff0000, v5
	v_pk_fma_f32 v[14:15], v[18:19], v[14:15], v[10:11] neg_lo:[1,0,0] neg_hi:[1,0,0]
	v_lshlrev_b32_e32 v10, 16, v8
	v_and_b32_e32 v11, 0xffff0000, v8
	v_lshlrev_b32_e32 v8, 16, v4
	v_and_b32_e32 v9, 0xffff0000, v4
	v_pk_fma_f32 v[4:5], v[18:19], v[8:9], v[10:11] neg_lo:[1,0,0] neg_hi:[1,0,0]
	v_lshlrev_b32_e32 v36, 16, v7
	v_and_b32_e32 v37, 0xffff0000, v7
	v_lshlrev_b32_e32 v40, 16, v6
	v_lshlrev_b32_e32 v6, 16, v2
	v_and_b32_e32 v7, 0xffff0000, v2
	v_lshlrev_b32_e32 v38, 16, v3
	v_and_b32_e32 v39, 0xffff0000, v3
	v_pk_fma_f32 v[2:3], v[18:19], v[6:7], v[40:41] neg_lo:[1,0,0] neg_hi:[1,0,0]
	v_pk_fma_f32 v[36:37], v[18:19], v[38:39], v[36:37] neg_lo:[1,0,0] neg_hi:[1,0,0]
	v_pk_mul_f32 v[6:7], v[2:3], v[2:3]
	v_pk_mul_f32 v[38:39], v[36:37], v[36:37]
	v_add_f32_e32 v0, v6, v7
	v_add_f32_e32 v0, v38, v0
	v_pk_mul_f32 v[24:25], v[4:5], v[4:5]
	v_add_f32_e32 v0, v39, v0
	v_add_f32_e32 v0, v24, v0
	v_pk_mul_f32 v[16:17], v[14:15], v[14:15]
	v_add_f32_e32 v0, v25, v0
	v_add_f32_e32 v0, v16, v0
	v_add_f32_e32 v0, v17, v0
	ds_bpermute_b32 v6, v26, v0
	s_waitcnt lgkmcnt(0)
	v_add_f32_e32 v0, v0, v6
	ds_bpermute_b32 v6, v27, v0
	s_waitcnt lgkmcnt(0)
	v_add_f32_e32 v0, v0, v6
	ds_bpermute_b32 v6, v28, v0
	s_waitcnt lgkmcnt(0)
	v_add_f32_e32 v0, v0, v6
	v_fmamk_f32 v0, v0, 0x3c800000, v217
	v_cmp_gt_f32_e32 vcc, s45, v0
	v_mul_f32_e32 v6, 0x4b800000, v0
	s_nop 0
	v_cndmask_b32_e32 v0, v0, v6, vcc
	v_rsq_f32_e32 v0, v0
	s_nop 0
	v_mul_f32_e32 v6, 0x45800000, v0
	v_cndmask_b32_e32 v0, v0, v6, vcc
	v_mul_f32_e32 v0, v35, v0
	v_pk_mul_f32 v[2:3], v[2:3], v[0:1] op_sel_hi:[1,0]
	v_pk_mul_f32 v[6:7], v[36:37], v[0:1] op_sel_hi:[1,0]
	v_pk_mul_f32 v[4:5], v[4:5], v[0:1] op_sel_hi:[1,0]
	v_cmp_lt_i32_e32 vcc, s101, v34
	s_or_b64 s[4:5], vcc, s[4:5]
	v_pk_mul_f32 v[4:5], v[164:165], v[4:5]
	v_pk_mul_f32 v[2:3], v[176:177], v[2:3]
	v_pk_mul_f32 v[6:7], v[178:179], v[6:7]
	v_pk_mul_f32 v[8:9], v[14:15], v[0:1] op_sel_hi:[1,0]
	v_cvt_pk_bf16_f32 v2, v2, v3
	v_pk_mul_f32 v[8:9], v[166:167], v[8:9]
	v_cvt_pk_bf16_f32 v3, v6, v7
	v_lshl_add_u64 v[6:7], v[12:13], 0, v[20:21]
	v_cvt_pk_bf16_f32 v4, v4, v5
	v_cvt_pk_bf16_f32 v5, v8, v9
	v_lshl_add_u64 v[6:7], v[6:7], 0, v[22:23]
	global_store_dwordx4 v[6:7], v[2:5], off offset:512
	s_andn2_b64 exec, exec, s[4:5]
	s_cbranch_execnz .LBB0_723
